# FoX skip-table builder issues its 4 KX probe loads and the gain loads together (one memory round trip per workgroup instead of five); otherwise v24
# speedup vs baseline: 1.0087x; 1.0087x over previous
; #define GAS __attribute__((address_space(1)))
; __device__ __forceinline__ unsigned f2bf(float f) { unsigned u = __builtin_bit_cast(unsigned, f); return (u + 0x7fffu + ((u >> 16) & 1u)) >> 16; }
; __device__ __forceinline__ fox::BlockRef fox_item(int L) { return fox_ref(L & 31, 15 - (L >> 5)); }
; __device__ __forceinline__ void p5_kx(Frame& F) {
;     ...
;         GAS v4u* kx = (GAS v4u*)(KX + ((size_t)bh * SEQ + sg * 512 + F.lane * 8) * 8);
; #pragma unroll
;         for (int i = 0; i < 8; ++i) { const float xj = -11.313708498984761f * (base + ls[i]);
;             const unsigned hi_ = f2bf(xj); const float r1 = xj - __builtin_bit_cast(float, hi_ << 16);
;             const unsigned mid_ = f2bf(r1); const float r2 = r1 - __builtin_bit_cast(float, mid_ << 16);
;             const unsigned lo_ = f2bf(r2);
;             v4u w; w.x = hi_ | (mid_ << 16); w.y = lo_; w.z = 0u; w.w = 0u; kx[i] = w; }
; __device__ __forceinline__ void p5_fox(Frame& F, char* lds) {
;     constexpr int TOTAL = BATCH * NH * (SEQ / 256);
;     __syncthreads();
;     if (F.tid == 0) { const unsigned a_ = __hip_atomic_fetch_add(F.ctl + CW_QUEUE, 1u, RLX_AGENT), b_ = __hip_atomic_fetch_add(F.ctl + CW_QUEUE, 1u, RLX_AGENT); F.MISC[16] = a_; F.MISC[17] = b_; }
;     __syncthreads();
;     int cur = (int)F.MISC[16]; if (cur >= TOTAL) return;
;     int nxt = (int)F.MISC[17];
;     const fox::Bases Bs{(const bf16*)(F.ws + WS_P), (const bf16*)(F.ws + WS_KX), (bf16*)(F.ws + WS_MIX)};
;     fox::Seam S;
;     { const fox::BlockRef c0 = fox_item(cur); fox::fox_prime<NPP, LDMIX>(Bs, c0, lds, S); }
.LBB0_1437:
	s_waitcnt vmcnt(0) lgkmcnt(0)
	s_barrier
	v_mbcnt_lo_u32_b32 v4, -1, 0
	v_mbcnt_hi_u32_b32 v4, -1, v4
	v_readfirstlane_b32 s40, v0
	s_lshr_b32 s40, s40, 6
	v_readlane_b32 s42, v252, 14
	v_readlane_b32 s43, v252, 15
	v_readlane_b32 s44, v252, 16
	v_readlane_b32 s45, v252, 17
	v_lshlrev_b32_e32 v5, 2, v4
	s_nop 4
	s_add_u32 s46, s82, 0x500000
	s_addc_u32 s47, s83, 0
	v_lshlrev_b32_e32 v24, 6, v4
	v_add_u32_e32 v24, -1, v24
	v_max_i32_e32 v24, 0, v24
	v_lshlrev_b32_e32 v24, 4, v24
	s_lshl_b32 s48, s40, 18
	s_add_u32 s64, s46, s48
	s_addc_u32 s65, s47, 0
	s_add_u32 s66, s64, 0x10000
	s_addc_u32 s67, s65, 0
	s_add_u32 s68, s64, 0x20000
	s_addc_u32 s69, s65, 0
	s_add_u32 s70, s64, 0x30000
	s_addc_u32 s71, s65, 0
	global_load_dwordx2 v[16:17], v24, s[64:65]
	global_load_dwordx2 v[18:19], v24, s[66:67]
	global_load_dwordx2 v[20:21], v24, s[68:69]
	global_load_dwordx2 v[22:23], v24, s[70:71]
	global_load_dword v6, v5, s[42:43]
	global_load_dword v7, v5, s[42:43] offset:256
	global_load_dword v8, v5, s[44:45]
	global_load_dword v9, v5, s[44:45] offset:256
	s_waitcnt vmcnt(0)
	v_and_b32_e32 v6, 0x7fffffff, v6
	v_and_b32_e32 v7, 0x7fffffff, v7
	v_and_b32_e32 v8, 0x7fffffff, v8
	v_and_b32_e32 v9, 0x7fffffff, v9
	v_max_u32_e32 v6, v6, v7
	v_max_u32_e32 v8, v8, v9
	v_xor_b32_e32 v10, 4, v5
	ds_bpermute_b32 v11, v10, v6
	ds_bpermute_b32 v12, v10, v8
	s_waitcnt lgkmcnt(0)
	v_max_u32_e32 v6, v6, v11
	v_max_u32_e32 v8, v8, v12
	v_xor_b32_e32 v10, 8, v5
	ds_bpermute_b32 v11, v10, v6
	ds_bpermute_b32 v12, v10, v8
	s_waitcnt lgkmcnt(0)
	v_max_u32_e32 v6, v6, v11
	v_max_u32_e32 v8, v8, v12
	v_xor_b32_e32 v10, 16, v5
	ds_bpermute_b32 v11, v10, v6
	ds_bpermute_b32 v12, v10, v8
	s_waitcnt lgkmcnt(0)
	v_max_u32_e32 v6, v6, v11
	v_max_u32_e32 v8, v8, v12
	v_xor_b32_e32 v10, 32, v5
	ds_bpermute_b32 v11, v10, v6
	ds_bpermute_b32 v12, v10, v8
	s_waitcnt lgkmcnt(0)
	v_max_u32_e32 v6, v6, v11
	v_max_u32_e32 v8, v8, v12
	v_xor_b32_e32 v10, 64, v5
	ds_bpermute_b32 v11, v10, v6
	ds_bpermute_b32 v12, v10, v8
	s_waitcnt lgkmcnt(0)
	v_max_u32_e32 v6, v6, v11
	v_max_u32_e32 v8, v8, v12
	v_xor_b32_e32 v10, 128, v5
	ds_bpermute_b32 v11, v10, v6
	ds_bpermute_b32 v12, v10, v8
	s_waitcnt lgkmcnt(0)
	v_max_u32_e32 v6, v6, v11
	v_max_u32_e32 v8, v8, v12
	v_mul_f32_e32 v6, v6, v8
	v_mov_b32_e32 v7, 0x41b80000
	v_mov_b32_e32 v8, 0x42e20000
	v_fma_f32 v6, v6, v7, v8
	v_mul_f32_e32 v6, 0x41351eb8, v6
	s_lshl_b32 s48, s40, 2
	s_mov_b32 s49, 0
.Lfsk_bh:
	s_add_i32 s50, s48, s49
	v_mov_b32_e32 v10, v16
	v_mov_b32_e32 v11, v17
	s_cmp_eq_u32 s49, 1
	s_cbranch_scc0 .Lfsk_n1
	v_mov_b32_e32 v10, v18
	v_mov_b32_e32 v11, v19
.Lfsk_n1:
	s_cmp_eq_u32 s49, 2
	s_cbranch_scc0 .Lfsk_n2
	v_mov_b32_e32 v10, v20
	v_mov_b32_e32 v11, v21
.Lfsk_n2:
	s_cmp_eq_u32 s49, 3
	s_cbranch_scc0 .Lfsk_n3
	v_mov_b32_e32 v10, v22
	v_mov_b32_e32 v11, v23
.Lfsk_n3:
	v_lshlrev_b32_e32 v12, 16, v10
	v_and_b32_e32 v13, 0xffff0000, v10
	v_lshlrev_b32_e32 v14, 16, v11
	v_add_f32_e32 v12, v12, v13
	v_add_f32_e32 v12, v12, v14
	s_lshl_b32 s62, s50, 6
	s_add_i32 s62, s62, 0x23400
	v_mov_b32_e32 v14, s62
	v_mov_b32_e32 v15, 0
	ds_write_b32 v14, v15
	s_mov_b32 s56, 1
